# baseline (speedup 1.0000x reference)
; template <int MODE> ...
;     ...
;       f32x4 s[2][4];
; #pragma unroll
;       for (int mt = 0; mt < 4; ++mt) {
;         s[0][mt] = (f32x4){0.f, 0.f, 0.f, 0.f};
;         s[1][mt] = (f32x4){0.f, 0.f, 0.f, 0.f};
;       }
; #pragma unroll
;       for (int ks = 0; ks < 4; ++ks)
; #pragma unroll
;         for (int mt = 0; mt < 4; ++mt) {
;           bf16x8 a = *(const bf16x8*)(Kt + (mt * 16 + c) * KT_STRIDE + ks * 32 + quad * 8);
;           s[0][mt] = __builtin_amdgcn_mfma_f32_16x16x32_bf16(a, qf[0][ks], s[0][mt], 0, 0, 0);
;           s[1][mt] = __builtin_amdgcn_mfma_f32_16x16x32_bf16(a, qf[1][ks], s[1][mt], 0, 0, 0);
;         }
;       const bool edge = (j == jhi) || (MODE == 1 && j == jhi - 8);
;       bf16x8 pb[2][2];
;       if (edge) {
; #pragma unroll
;         for (int qs = 0; qs < 2; ++qs) {
;           const int key0 = j * 64 + quad * 4;
;           const int tk = tok[qs];
; #pragma unroll
;           for (int mt = 0; mt < 4; ++mt)
; #pragma unroll
;             for (int jj = 0; jj < 4; ++jj) {
;               const int key = key0 + mt * 16 + jj;
;               bool valid = key <= tk;
;               if (MODE == 1) valid = valid && (key > tk - 512);
;               s[qs][mt][jj] = valid ? s[qs][mt][jj] : RAW_MASKED;
;             }
;         }
;       }
;       float alpha[2];
; #pragma unroll
;       for (int qs = 0; qs < 2; ++qs) {
;         const bool sel = (MODE == 1) ? true : (bool)((mymask[qs] >> j) & 1ull);
;         float mx4[4];
; #pragma unroll
;         for (int mt = 0; mt < 4; ++mt)
;           mx4[mt] = fmaxf(fmaxf(s[qs][mt][0], s[qs][mt][1]), fmaxf(s[qs][mt][2], s[qs][mt][3]));
;         float mx = fmaxf(fmaxf(mx4[0], mx4[1]), fmaxf(mx4[2], mx4[3]));
;         mx = sel ? mx * SCL : -1e30f;
;         mx = quad_max(mx);
;         const float m_new = (mx > m_run[qs] + RESCALE_THR) ? mx : m_run[qs];
;         alpha[qs] = __builtin_amdgcn_exp2f(m_run[qs] - m_new);
;         m_run[qs] = m_new;
;     ...
;       if (__ballot(alpha[0] != 1.0f || alpha[1] != 1.0f) != 0ull) {
; #pragma unroll
.LBB0_323:
	v_add_co_u32_e32 v100, vcc, 0xf4000, v144
	s_lshl_b64 s[8:9], 1, s58
	global_load_dwordx4 v[96:99], v[144:145], off offset:2048
	v_addc_co_u32_e32 v101, vcc, 0, v145, vcc
	v_add_co_u32_e32 v108, vcc, 0x80000, v146
	s_and_b32 s34, s58, 1
	global_load_dwordx4 v[100:103], v[100:101], off offset:2048
	v_addc_co_u32_e32 v109, vcc, 0, v147, vcc
	global_load_dwordx4 v[104:107], v[146:147], off offset:128
	global_load_dwordx4 v[108:111], v[108:109], off offset:128
	s_and_b64 s[10:11], s[8:9], s[16:17]
	s_cmp_eq_u64 s[10:11], 0
	s_cbranch_scc1 .LBB0_322
	s_mul_i32 s10, s34, 0x8c00
	v_add_u32_e32 v167, s10, v178
	v_add_u32_e32 v166, v167, v176
	ds_read_b128 v[112:115], v166
	ds_read_b128 v[116:119], v166 offset:64
	ds_read_b128 v[124:127], v166 offset:4352
	ds_read_b128 v[132:135], v166 offset:4416
	v_and_b32_e32 v169, s9, v163
	v_and_b32_e32 v168, s8, v162
	s_waitcnt lgkmcnt(3)
	v_mfma_f32_16x16x32_bf16 v[120:123], v[112:115], v[8:11], 0
	v_cmp_eq_u64_e64 s[10:11], 0, v[168:169]
	s_waitcnt lgkmcnt(1)
	v_mfma_f32_16x16x32_bf16 v[128:131], v[124:127], v[8:11], 0
	v_mfma_f32_16x16x32_bf16 v[136:139], v[124:127], v[24:27], 0
	ds_read_b128 v[124:127], v166 offset:8704
	ds_read_b128 v[148:151], v166 offset:8768
	ds_read_b128 v[156:159], v166 offset:13056
	ds_read_b128 v[196:199], v166 offset:13120
	ds_read_b128 v[204:207], v166 offset:128
	ds_read_b128 v[218:221], v166 offset:192
	v_mfma_f32_16x16x32_bf16 v[120:123], v[116:119], v[0:3], v[120:123]
	ds_read_b128 v[222:225], v166 offset:4480
	ds_read_b128 v[226:229], v166 offset:4544
	ds_read_b128 v[230:233], v166 offset:8832
	ds_read_b128 v[234:237], v166 offset:8896
	ds_read_b128 v[242:245], v166 offset:13184
	ds_read_b128 v[246:249], v166 offset:13248
	s_waitcnt lgkmcnt(11)
	v_mfma_f32_16x16x32_bf16 v[140:143], v[124:127], v[8:11], 0
	v_mfma_f32_16x16x32_bf16 v[152:155], v[124:127], v[24:27], 0
	s_waitcnt lgkmcnt(9)
	v_mfma_f32_16x16x32_bf16 v[124:127], v[156:159], v[8:11], 0
	v_mfma_f32_16x16x32_bf16 v[128:131], v[132:135], v[0:3], v[128:131]
	s_waitcnt lgkmcnt(7)
	v_mfma_f32_16x16x32_bf16 v[120:123], v[204:207], v[4:7], v[120:123]
	v_mfma_f32_16x16x32_bf16 v[140:143], v[148:151], v[0:3], v[140:143]
	v_mfma_f32_16x16x32_bf16 v[200:203], v[196:199], v[0:3], v[124:127]
	s_waitcnt lgkmcnt(5)
	v_mfma_f32_16x16x32_bf16 v[124:127], v[222:225], v[4:7], v[128:131]
	v_mfma_f32_16x16x32_bf16 v[128:131], v[218:221], v[12:15], v[120:123]
	s_waitcnt lgkmcnt(3)
	v_mfma_f32_16x16x32_bf16 v[238:241], v[230:233], v[4:7], v[140:143]
	v_mfma_f32_16x16x32_bf16 v[140:143], v[226:229], v[12:15], v[124:127]
	s_nop 4
	v_max_f32_e32 v120, v130, v131
	v_max3_f32 v166, v128, v129, v120
	s_waitcnt lgkmcnt(2)
	v_mfma_f32_16x16x32_bf16 v[124:127], v[234:237], v[12:15], v[238:241]
	v_max_f32_e32 v120, v142, v143
	v_max3_f32 v183, v140, v141, v120
	s_waitcnt lgkmcnt(1)
	v_mfma_f32_16x16x32_bf16 v[120:123], v[242:245], v[4:7], v[200:203]
	s_nop 1
	s_waitcnt lgkmcnt(0)
	v_mfma_f32_16x16x32_bf16 v[120:123], v[246:249], v[12:15], v[120:123]
	v_max_f32_e32 v191, v124, v125
	v_mfma_f32_16x16x32_bf16 v[112:115], v[112:115], v[24:27], 0
	v_max_f32_e32 v200, v126, v127
	s_nop 1
	s_nop 2
	v_max_f32_e32 v202, v122, v122
	v_max_f32_e32 v201, v202, v123
	v_max3_f32 v201, v120, v121, v201
	v_mfma_f32_16x16x32_bf16 v[112:115], v[116:119], v[16:19], v[112:115]
	v_max3_f32 v116, v191, v200, v201
	v_max3_f32 v116, v166, v183, v116
	v_mul_f32_e32 v166, 0x3e0293ee, v116
	v_mfma_f32_16x16x32_bf16 v[116:119], v[132:135], v[16:19], v[136:139]
	v_cndmask_b32_e64 v132, v166, v214, s[10:11]
	v_mov_b32_e32 v133, v132
	s_nop 1
	v_permlane16_swap_b32_e32 v132, v133
	v_mfma_f32_16x16x32_bf16 v[112:115], v[204:207], v[20:23], v[112:115]
	v_max_f32_e32 v132, v132, v133
	v_mfma_f32_16x16x32_bf16 v[156:159], v[156:159], v[24:27], 0
	v_mov_b32_e32 v133, v132
	s_nop 1
	v_permlane32_swap_b32_e32 v132, v133
	v_mfma_f32_16x16x32_bf16 v[116:119], v[222:225], v[20:23], v[116:119]
	v_mfma_f32_16x16x32_bf16 v[136:139], v[218:221], v[28:31], v[112:115]
	v_mfma_f32_16x16x32_bf16 v[148:151], v[148:151], v[16:19], v[152:155]
	v_mfma_f32_16x16x32_bf16 v[152:155], v[196:199], v[16:19], v[156:159]
	s_nop 5
	v_max_f32_e32 v112, v138, v139
	v_max_f32_e32 v158, v132, v133
	v_mfma_f32_16x16x32_bf16 v[132:135], v[226:229], v[28:31], v[116:119]
	v_max3_f32 v159, v136, v137, v112
	v_and_b32_e32 v157, s9, v161
	v_and_b32_e32 v156, s8, v160
	v_mfma_f32_16x16x32_bf16 v[112:115], v[230:233], v[20:23], v[148:151]
	v_cmp_eq_u64_e64 s[8:9], 0, v[156:157]
	s_nop 2
	v_max_f32_e32 v116, v134, v135
	v_max3_f32 v148, v132, v133, v116
	v_mfma_f32_16x16x32_bf16 v[116:119], v[234:237], v[28:31], v[112:115]
	s_nop 7
	v_max_f32_e32 v149, v116, v117
	v_mfma_f32_16x16x32_bf16 v[112:115], v[242:245], v[20:23], v[152:155]
	v_max_f32_e32 v150, v118, v119
	v_mfma_f32_16x16x32_bf16 v[112:115], v[246:249], v[28:31], v[112:115]
	s_nop 7
	v_max_f32_e32 v152, v114, v114
	v_max_f32_e32 v151, v152, v115
	v_max3_f32 v151, v112, v113, v151
	v_max3_f32 v149, v149, v150, v151
	v_max3_f32 v148, v159, v148, v149
	v_mul_f32_e32 v148, 0x3e0293ee, v148
	v_cndmask_b32_e64 v148, v148, v214, s[8:9]
	v_mov_b32_e32 v149, v148
	s_nop 1
	v_permlane16_swap_b32_e32 v148, v149
	v_max_f32_e32 v148, v148, v149
	v_mov_b32_e32 v149, v148
	s_nop 1
	v_permlane32_swap_b32_e32 v148, v149
	v_max_f32_e32 v150, v148, v149
	v_add_f32_e32 v148, s46, v164
	v_add_f32_e32 v149, s46, v165
	s_nop 0
	v_cmp_gt_f32_e64 s[12:13], v150, v149
	s_nop 1
	v_cndmask_b32_e64 v149, v165, v150, s[12:13]
	v_cmp_gt_f32_e32 vcc, v158, v148
	s_nop 1
	v_cndmask_b32_e32 v148, v164, v158, vcc
	v_sub_f32_e32 v150, v164, v148
	v_sub_f32_e32 v151, v165, v149
	s_nop 0
	v_exp_f32_e32 v150, v150
	v_exp_f32_e32 v151, v151
	s_or_b64 vcc, vcc, s[12:13]
	s_cbranch_vccz .LBB0_321
; template <int MODE> ...
;     ...
;       if (__ballot(alpha[0] != 1.0f || alpha[1] != 1.0f) != 0ull) {
; #pragma unroll
;         for (int qs = 0; qs < 2; ++qs)
; #pragma unroll
;           for (int dt = 0; dt < 8; ++dt) {
;             o[qs][dt][0] *= alpha[qs]; o[qs][dt][1] *= alpha[qs]; o[qs][dt][2] *= alpha[qs]; o[qs][dt][3] *= alpha[qs];
;           }
;       }
	v_mov_b32_e32 v152, v151
	v_pk_mul_f32 v[92:93], v[92:93], v[150:151] op_sel_hi:[1,0]
	v_pk_mul_f32 v[94:95], v[94:95], v[150:151] op_sel_hi:[1,0]
	v_pk_mul_f32 v[84:85], v[84:85], v[150:151] op_sel_hi:[1,0]
	v_pk_mul_f32 v[86:87], v[86:87], v[150:151] op_sel_hi:[1,0]
	v_pk_mul_f32 v[76:77], v[76:77], v[150:151] op_sel_hi:[1,0]
	v_pk_mul_f32 v[78:79], v[78:79], v[150:151] op_sel_hi:[1,0]
	v_pk_mul_f32 v[68:69], v[68:69], v[150:151] op_sel_hi:[1,0]
	v_pk_mul_f32 v[70:71], v[70:71], v[150:151] op_sel_hi:[1,0]
	v_pk_mul_f32 v[56:57], v[56:57], v[150:151] op_sel_hi:[1,0]
	v_pk_mul_f32 v[58:59], v[58:59], v[150:151] op_sel_hi:[1,0]
	v_pk_mul_f32 v[44:45], v[44:45], v[150:151] op_sel_hi:[1,0]
	v_pk_mul_f32 v[46:47], v[46:47], v[150:151] op_sel_hi:[1,0]
	v_pk_mul_f32 v[36:37], v[36:37], v[150:151] op_sel_hi:[1,0]
	v_pk_mul_f32 v[38:39], v[38:39], v[150:151] op_sel_hi:[1,0]
	v_pk_mul_f32 v[60:61], v[60:61], v[150:151] op_sel_hi:[1,0]
	v_pk_mul_f32 v[62:63], v[62:63], v[150:151] op_sel_hi:[1,0]
	v_pk_mul_f32 v[90:91], v[90:91], v[152:153] op_sel_hi:[1,0]
	v_pk_mul_f32 v[88:89], v[88:89], v[152:153] op_sel_hi:[1,0]
	v_pk_mul_f32 v[82:83], v[82:83], v[152:153] op_sel_hi:[1,0]
	v_pk_mul_f32 v[80:81], v[80:81], v[152:153] op_sel_hi:[1,0]
	v_pk_mul_f32 v[74:75], v[74:75], v[152:153] op_sel_hi:[1,0]
	v_pk_mul_f32 v[72:73], v[72:73], v[152:153] op_sel_hi:[1,0]
	v_pk_mul_f32 v[66:67], v[66:67], v[152:153] op_sel_hi:[1,0]
	v_pk_mul_f32 v[64:65], v[64:65], v[152:153] op_sel_hi:[1,0]
	v_pk_mul_f32 v[54:55], v[54:55], v[152:153] op_sel_hi:[1,0]
	v_pk_mul_f32 v[52:53], v[52:53], v[152:153] op_sel_hi:[1,0]
	v_pk_mul_f32 v[42:43], v[42:43], v[152:153] op_sel_hi:[1,0]
	v_pk_mul_f32 v[40:41], v[40:41], v[152:153] op_sel_hi:[1,0]
	v_pk_mul_f32 v[34:35], v[34:35], v[152:153] op_sel_hi:[1,0]
	v_pk_mul_f32 v[32:33], v[32:33], v[152:153] op_sel_hi:[1,0]
	v_pk_mul_f32 v[50:51], v[50:51], v[152:153] op_sel_hi:[1,0]
	v_pk_mul_f32 v[48:49], v[48:49], v[152:153] op_sel_hi:[1,0]
	s_branch .LBB0_321

; template <int MODE> ...
;     ...
;       for (int qs = 0; qs < 2; ++qs) {
;         const bool sel = (MODE == 1) ? true : (bool)((mymask[qs] >> j) & 1ull);
;         float mx4[4];
; #pragma unroll
;         for (int mt = 0; mt < 4; ++mt)
;           mx4[mt] = fmaxf(fmaxf(s[qs][mt][0], s[qs][mt][1]), fmaxf(s[qs][mt][2], s[qs][mt][3]));
;         float mx = fmaxf(fmaxf(mx4[0], mx4[1]), fmaxf(mx4[2], mx4[3]));
;         mx = sel ? mx * SCL : -1e30f;
;         mx = quad_max(mx);
;         const float m_new = (mx > m_run[qs] + RESCALE_THR) ? mx : m_run[qs];
;         alpha[qs] = __builtin_amdgcn_exp2f(m_run[qs] - m_new);
;         m_run[qs] = m_new;
;         const float negm = sel ? -m_new : -1e30f;
;         float ps4[4];
; #pragma unroll
;         for (int mt = 0; mt < 4; ++mt) {
; #pragma unroll
;           for (int jj = 0; jj < 4; ++jj) s[qs][mt][jj] = __builtin_amdgcn_exp2f(fmaf(s[qs][mt][jj], SCL, negm));
;           ps4[mt] = (s[qs][mt][0] + s[qs][mt][1]) + (s[qs][mt][2] + s[qs][mt][3]);
;         }
;         l_run[qs] = l_run[qs] * alpha[qs] + ((ps4[0] + ps4[1]) + (ps4[2] + ps4[3]));
; #pragma unroll
;         for (int kk = 0; kk < 2; ++kk) {
;           uint4 pk;
;           pk.x = pack2(s[qs][2 * kk][0], s[qs][2 * kk][1]);
;           pk.y = pack2(s[qs][2 * kk][2], s[qs][2 * kk][3]);
;           pk.z = pack2(s[qs][2 * kk + 1][0], s[qs][2 * kk + 1][1]);
;           pk.w = pack2(s[qs][2 * kk + 1][2], s[qs][2 * kk + 1][3]);
;           pb[qs][kk] = *reinterpret_cast<bf16x8*>(&pk);
;         }
;       }
;       if (__ballot(alpha[0] != 1.0f || alpha[1] != 1.0f) != 0ull) {
; #pragma unroll
;         for (int qs = 0; qs < 2; ++qs)
; #pragma unroll
;           for (int dt = 0; dt < 8; ++dt) {
;             o[qs][dt][0] *= alpha[qs]; o[qs][dt][1] *= alpha[qs]; o[qs][dt][2] *= alpha[qs]; o[qs][dt][3] *= alpha[qs];
;           }
;       }
.LBB0_341:
	v_max_f32_e32 v154, v142, v143
	v_max_f32_e32 v155, v138, v139
	s_nop 0
	v_max_f32_e32 v156, v116, v117
	v_max_f32_e32 v158, v118, v119
	s_nop 0
	v_max_f32_e32 v159, v126, v127
	v_max3_f32 v159, v124, v125, v159
	v_max3_f32 v154, v140, v141, v154
	v_max3_f32 v155, v136, v137, v155
	v_max3_f32 v156, v156, v158, v159
	v_max3_f32 v154, v154, v155, v156
	v_mul_f32_e32 v154, 0x3e0293ee, v154
	v_mov_b32_e32 v155, v154
	s_nop 1
	v_permlane16_swap_b32_e32 v154, v155
	v_max_f32_e32 v154, v154, v155
	v_mov_b32_e32 v155, v154
	s_nop 1
	v_permlane32_swap_b32_e32 v154, v155
	v_max_f32_e32 v156, v154, v155
	v_max_f32_e32 v154, v134, v135
	v_max_f32_e32 v155, v130, v131
	v_max_f32_e32 v158, v112, v113
	v_max_f32_e32 v159, v114, v115
	v_max_f32_e32 v161, v122, v122
	v_max_f32_e32 v160, v161, v123
	v_max3_f32 v160, v120, v121, v160
	v_max3_f32 v154, v132, v133, v154
	v_max3_f32 v155, v128, v129, v155
	v_max3_f32 v158, v158, v159, v160
	v_max3_f32 v154, v154, v155, v158
	v_mul_f32_e32 v154, 0x3e0293ee, v154
	v_mov_b32_e32 v155, v154
	s_nop 1
	v_permlane16_swap_b32_e32 v154, v155
	v_max_f32_e32 v154, v154, v155
	v_mov_b32_e32 v155, v154
	s_nop 1
	v_permlane32_swap_b32_e32 v154, v155
	v_mov_b32_e32 v152, v150
	v_mov_b32_e32 v153, v151
	v_max_f32_e32 v158, v154, v155
	v_add_f32_e32 v154, s46, v152
	v_add_f32_e32 v155, s46, v153
	s_nop 0
	v_cmp_gt_f32_e64 s[8:9], v158, v155
	s_nop 1
	v_cndmask_b32_e64 v151, v151, v158, s[8:9]
	v_cmp_gt_f32_e32 vcc, v156, v154
	s_nop 1
	v_cndmask_b32_e32 v150, v150, v156, vcc
	v_sub_f32_e32 v152, v152, v150
	v_sub_f32_e32 v153, v153, v151
	s_nop 0
	v_exp_f32_e32 v152, v152
	v_exp_f32_e32 v153, v153
	s_or_b64 vcc, vcc, s[8:9]
	s_cbranch_vccz .LBB0_343
	v_mov_b32_e32 v154, v153
	v_pk_mul_f32 v[92:93], v[92:93], v[152:153] op_sel_hi:[1,0]
	v_pk_mul_f32 v[94:95], v[94:95], v[152:153] op_sel_hi:[1,0]
	v_pk_mul_f32 v[88:89], v[88:89], v[152:153] op_sel_hi:[1,0]
	v_pk_mul_f32 v[90:91], v[90:91], v[152:153] op_sel_hi:[1,0]
	v_pk_mul_f32 v[84:85], v[84:85], v[152:153] op_sel_hi:[1,0]
	v_pk_mul_f32 v[86:87], v[86:87], v[152:153] op_sel_hi:[1,0]
	v_pk_mul_f32 v[80:81], v[80:81], v[152:153] op_sel_hi:[1,0]
	v_pk_mul_f32 v[82:83], v[82:83], v[152:153] op_sel_hi:[1,0]
	v_pk_mul_f32 v[76:77], v[76:77], v[152:153] op_sel_hi:[1,0]
	v_pk_mul_f32 v[78:79], v[78:79], v[152:153] op_sel_hi:[1,0]
	v_pk_mul_f32 v[72:73], v[72:73], v[152:153] op_sel_hi:[1,0]
	v_pk_mul_f32 v[74:75], v[74:75], v[152:153] op_sel_hi:[1,0]
	v_pk_mul_f32 v[68:69], v[68:69], v[152:153] op_sel_hi:[1,0]
	v_pk_mul_f32 v[70:71], v[70:71], v[152:153] op_sel_hi:[1,0]
	v_pk_mul_f32 v[64:65], v[64:65], v[152:153] op_sel_hi:[1,0]
	v_pk_mul_f32 v[66:67], v[66:67], v[152:153] op_sel_hi:[1,0]
	v_pk_mul_f32 v[62:63], v[62:63], v[154:155] op_sel_hi:[1,0]
	v_pk_mul_f32 v[60:61], v[60:61], v[154:155] op_sel_hi:[1,0]
	v_pk_mul_f32 v[58:59], v[58:59], v[154:155] op_sel_hi:[1,0]
	v_pk_mul_f32 v[56:57], v[56:57], v[154:155] op_sel_hi:[1,0]
	v_pk_mul_f32 v[54:55], v[54:55], v[154:155] op_sel_hi:[1,0]
	v_pk_mul_f32 v[52:53], v[52:53], v[154:155] op_sel_hi:[1,0]
	v_pk_mul_f32 v[50:51], v[50:51], v[154:155] op_sel_hi:[1,0]
	v_pk_mul_f32 v[48:49], v[48:49], v[154:155] op_sel_hi:[1,0]
	v_pk_mul_f32 v[46:47], v[46:47], v[154:155] op_sel_hi:[1,0]
	v_pk_mul_f32 v[44:45], v[44:45], v[154:155] op_sel_hi:[1,0]
	v_pk_mul_f32 v[42:43], v[42:43], v[154:155] op_sel_hi:[1,0]
	v_pk_mul_f32 v[40:41], v[40:41], v[154:155] op_sel_hi:[1,0]
	v_pk_mul_f32 v[38:39], v[38:39], v[154:155] op_sel_hi:[1,0]
	v_pk_mul_f32 v[36:37], v[36:37], v[154:155] op_sel_hi:[1,0]
	v_pk_mul_f32 v[34:35], v[34:35], v[154:155] op_sel_hi:[1,0]
	v_pk_mul_f32 v[32:33], v[32:33], v[154:155] op_sel_hi:[1,0]

; template <int MODE> ...
;     ...
;       f32x4 s[2][4];
; #pragma unroll
;       for (int mt = 0; mt < 4; ++mt) {
;         s[0][mt] = (f32x4){0.f, 0.f, 0.f, 0.f};
;         s[1][mt] = (f32x4){0.f, 0.f, 0.f, 0.f};
;       }
; #pragma unroll
;       for (int ks = 0; ks < 4; ++ks)
; #pragma unroll
;         for (int mt = 0; mt < 4; ++mt) {
;           bf16x8 a = *(const bf16x8*)(Kt + (mt * 16 + c) * KT_STRIDE + ks * 32 + quad * 8);
;           s[0][mt] = __builtin_amdgcn_mfma_f32_16x16x32_bf16(a, qf[0][ks], s[0][mt], 0, 0, 0);
;           s[1][mt] = __builtin_amdgcn_mfma_f32_16x16x32_bf16(a, qf[1][ks], s[1][mt], 0, 0, 0);
;         }
;       const bool edge = (j == jhi) || (MODE == 1 && j == jhi - 8);
;       bf16x8 pb[2][2];
;       if (edge) {
; #pragma unroll
;         for (int qs = 0; qs < 2; ++qs) {
;           const int key0 = j * 64 + quad * 4;
;           const int tk = tok[qs];
; #pragma unroll
;           for (int mt = 0; mt < 4; ++mt)
; #pragma unroll
;             for (int jj = 0; jj < 4; ++jj) {
;               const int key = key0 + mt * 16 + jj;
;               bool valid = key <= tk;
;               if (MODE == 1) valid = valid && (key > tk - 512);
;               s[qs][mt][jj] = valid ? s[qs][mt][jj] : RAW_MASKED;
;             }
;         }
;       }
;       float alpha[2];
; #pragma unroll
;       for (int qs = 0; qs < 2; ++qs) {
;         const bool sel = (MODE == 1) ? true : (bool)((mymask[qs] >> j) & 1ull);
;         float mx4[4];
; #pragma unroll
;         for (int mt = 0; mt < 4; ++mt)
;           mx4[mt] = fmaxf(fmaxf(s[qs][mt][0], s[qs][mt][1]), fmaxf(s[qs][mt][2], s[qs][mt][3]));
;         float mx = fmaxf(fmaxf(mx4[0], mx4[1]), fmaxf(mx4[2], mx4[3]));
;         mx = sel ? mx * SCL : -1e30f;
;         mx = quad_max(mx);
;         const float m_new = (mx > m_run[qs] + RESCALE_THR) ? mx : m_run[qs];
;         alpha[qs] = __builtin_amdgcn_exp2f(m_run[qs] - m_new);
;         m_run[qs] = m_new;
;     ...
;       if (__ballot(alpha[0] != 1.0f || alpha[1] != 1.0f) != 0ull) {
; #pragma unroll
.LBB0_659:
	v_add_co_u32_e32 v100, vcc, 0xf4000, v144
	s_lshl_b64 s[10:11], 1, s60
	global_load_dwordx4 v[96:99], v[144:145], off offset:2048
	v_addc_co_u32_e32 v101, vcc, 0, v145, vcc
	v_add_co_u32_e32 v108, vcc, 0x80000, v146
	s_and_b32 s8, s60, 1
	global_load_dwordx4 v[100:103], v[100:101], off offset:2048
	v_addc_co_u32_e32 v109, vcc, 0, v147, vcc
	global_load_dwordx4 v[104:107], v[146:147], off offset:128
	global_load_dwordx4 v[108:111], v[108:109], off offset:128
	s_and_b64 s[6:7], s[10:11], s[16:17]
	s_cmp_eq_u64 s[6:7], 0
	s_cbranch_scc1 .LBB0_658
	s_mul_i32 s6, s8, 0x8c00
	v_add_u32_e32 v157, s6, v174
	v_add_u32_e32 v156, v157, v171
	ds_read_b128 v[112:115], v156
	ds_read_b128 v[148:151], v156 offset:64
	ds_read_b128 v[120:123], v156 offset:4352
	ds_read_b128 v[128:131], v156 offset:8704
	ds_read_b128 v[136:139], v156 offset:13056
	s_waitcnt lgkmcnt(4)
	v_mfma_f32_16x16x32_bf16 v[116:119], v[112:115], v[8:11], 0
	v_mfma_f32_16x16x32_bf16 v[112:115], v[112:115], v[24:27], 0
	s_waitcnt lgkmcnt(3)
	v_mfma_f32_16x16x32_bf16 v[116:119], v[148:151], v[0:3], v[116:119]
	v_mfma_f32_16x16x32_bf16 v[112:115], v[148:151], v[16:19], v[112:115]
	ds_read_b128 v[148:151], v156 offset:4416
	s_waitcnt lgkmcnt(3)
	v_mfma_f32_16x16x32_bf16 v[124:127], v[120:123], v[8:11], 0
	v_mfma_f32_16x16x32_bf16 v[120:123], v[120:123], v[24:27], 0
	s_waitcnt lgkmcnt(0)
	v_mfma_f32_16x16x32_bf16 v[124:127], v[148:151], v[0:3], v[124:127]
	v_mfma_f32_16x16x32_bf16 v[120:123], v[148:151], v[16:19], v[120:123]
	ds_read_b128 v[148:151], v156 offset:8768
	v_mfma_f32_16x16x32_bf16 v[132:135], v[128:131], v[8:11], 0
	v_mfma_f32_16x16x32_bf16 v[128:131], v[128:131], v[24:27], 0
	s_waitcnt lgkmcnt(0)
	v_mfma_f32_16x16x32_bf16 v[132:135], v[148:151], v[0:3], v[132:135]
	v_mfma_f32_16x16x32_bf16 v[128:131], v[148:151], v[16:19], v[128:131]
	ds_read_b128 v[148:151], v156 offset:13120
	v_mfma_f32_16x16x32_bf16 v[140:143], v[136:139], v[8:11], 0
	v_mfma_f32_16x16x32_bf16 v[136:139], v[136:139], v[24:27], 0
	s_waitcnt lgkmcnt(0)
	v_mfma_f32_16x16x32_bf16 v[140:143], v[148:151], v[0:3], v[140:143]
	v_mfma_f32_16x16x32_bf16 v[136:139], v[148:151], v[16:19], v[136:139]
	ds_read_b128 v[148:151], v156 offset:128
	s_waitcnt lgkmcnt(0)
	v_mfma_f32_16x16x32_bf16 v[116:119], v[148:151], v[4:7], v[116:119]
	v_mfma_f32_16x16x32_bf16 v[112:115], v[148:151], v[20:23], v[112:115]
	ds_read_b128 v[148:151], v156 offset:4480
	s_waitcnt lgkmcnt(0)
	v_mfma_f32_16x16x32_bf16 v[124:127], v[148:151], v[4:7], v[124:127]
	v_mfma_f32_16x16x32_bf16 v[120:123], v[148:151], v[20:23], v[120:123]
	ds_read_b128 v[148:151], v156 offset:8832
	s_waitcnt lgkmcnt(0)
	v_mfma_f32_16x16x32_bf16 v[152:155], v[148:151], v[4:7], v[132:135]
	v_mfma_f32_16x16x32_bf16 v[148:151], v[148:151], v[20:23], v[128:131]
	s_nop 2
	ds_read_b128 v[128:131], v156 offset:13184
	s_waitcnt lgkmcnt(0)
	v_mfma_f32_16x16x32_bf16 v[176:179], v[128:131], v[4:7], v[140:143]
	v_mfma_f32_16x16x32_bf16 v[196:199], v[128:131], v[20:23], v[136:139]
	ds_read_b128 v[128:131], v156 offset:192
	s_waitcnt lgkmcnt(0)
	v_mfma_f32_16x16x32_bf16 v[132:135], v[128:131], v[28:31], v[112:115]
	s_nop 2
	ds_read_b128 v[112:115], v156 offset:4544
	v_mfma_f32_16x16x32_bf16 v[136:139], v[128:131], v[12:15], v[116:119]
	s_nop 2
	ds_read_b128 v[116:119], v156 offset:13248
	s_waitcnt lgkmcnt(1)
	v_mfma_f32_16x16x32_bf16 v[140:143], v[112:115], v[12:15], v[124:127]
	v_mfma_f32_16x16x32_bf16 v[128:131], v[112:115], v[28:31], v[120:123]
	ds_read_b128 v[112:115], v156 offset:8896
	s_waitcnt lgkmcnt(0)
	v_mfma_f32_16x16x32_bf16 v[124:127], v[112:115], v[12:15], v[152:155]
	s_nop 3
	s_nop 2
	v_mfma_f32_16x16x32_bf16 v[112:115], v[112:115], v[28:31], v[148:151]
	v_mfma_f32_16x16x32_bf16 v[120:123], v[116:119], v[12:15], v[176:179]
	s_nop 0
	s_nop 0
	v_max_f32_e32 v150, v138, v139
	v_max_f32_e32 v151, v142, v143
	v_max_f32_e32 v152, v124, v125
	v_max_f32_e32 v153, v126, v127
	s_nop 1
	v_max_f32_e32 v154, v122, v123
	v_and_b32_e32 v149, s11, v163
	v_and_b32_e32 v148, s10, v162
	v_max3_f32 v154, v120, v121, v154
	v_max3_f32 v150, v136, v137, v150
	v_max3_f32 v151, v140, v141, v151
	v_cmp_eq_u64_e64 s[6:7], 0, v[148:149]
	v_max3_f32 v148, v152, v153, v154
	v_max3_f32 v148, v150, v151, v148
	v_mul_f32_e32 v148, 0x3e0293ee, v148
	v_cndmask_b32_e64 v148, v148, v214, s[6:7]
	v_mov_b32_e32 v149, v148
	v_mfma_f32_16x16x32_bf16 v[116:119], v[116:119], v[28:31], v[196:199]
	s_nop 0
	v_permlane16_swap_b32_e32 v148, v149
	v_max_f32_e32 v151, v134, v135
	v_max_f32_e32 v148, v148, v149
	v_max_f32_e32 v152, v130, v131
	v_mov_b32_e32 v149, v148
	v_max_f32_e32 v153, v112, v113
	s_nop 0
	v_permlane32_swap_b32_e32 v148, v149
	v_max_f32_e32 v154, v114, v115
	v_max_f32_e32 v156, v118, v118
	v_max_f32_e32 v155, v156, v119
	v_max_f32_e32 v150, v148, v149
	v_and_b32_e32 v149, s11, v161
	v_and_b32_e32 v148, s10, v160
	v_max3_f32 v155, v116, v117, v155
	v_max3_f32 v151, v132, v133, v151
	v_max3_f32 v152, v128, v129, v152
	v_cmp_eq_u64_e64 s[10:11], 0, v[148:149]
	v_max3_f32 v148, v153, v154, v155
	v_max3_f32 v148, v151, v152, v148
	v_mul_f32_e32 v148, 0x3e0293ee, v148
	v_cndmask_b32_e64 v148, v148, v214, s[10:11]
	v_mov_b32_e32 v149, v148
	s_nop 1
	v_permlane16_swap_b32_e32 v148, v149
	v_max_f32_e32 v148, v148, v149
	v_mov_b32_e32 v149, v148
	s_nop 1
	v_permlane32_swap_b32_e32 v148, v149
	v_max_f32_e32 v151, v148, v149
	v_add_f32_e32 v148, s48, v164
	v_add_f32_e32 v149, s48, v165
	s_nop 0
	v_cmp_gt_f32_e32 vcc, v150, v148
	v_cmp_gt_f32_e64 s[12:13], v151, v149
	s_nop 0
	v_cndmask_b32_e32 v148, v164, v150, vcc
	v_cndmask_b32_e64 v149, v165, v151, s[12:13]
	v_sub_f32_e32 v150, v164, v148
	v_sub_f32_e32 v151, v165, v149
	s_nop 0
	v_exp_f32_e32 v150, v150
	v_exp_f32_e32 v151, v151
	s_or_b64 vcc, vcc, s[12:13]
	s_cbranch_vccz .LBB0_657
; template <int MODE> ...
;     ...
;       if (__ballot(alpha[0] != 1.0f || alpha[1] != 1.0f) != 0ull) {
; #pragma unroll
;         for (int qs = 0; qs < 2; ++qs)
; #pragma unroll
;           for (int dt = 0; dt < 8; ++dt) {
;             o[qs][dt][0] *= alpha[qs]; o[qs][dt][1] *= alpha[qs]; o[qs][dt][2] *= alpha[qs]; o[qs][dt][3] *= alpha[qs];
;           }
;       }
	v_mov_b32_e32 v152, v151
	v_pk_mul_f32 v[92:93], v[92:93], v[150:151] op_sel_hi:[1,0]
	v_pk_mul_f32 v[94:95], v[94:95], v[150:151] op_sel_hi:[1,0]
	v_pk_mul_f32 v[84:85], v[84:85], v[150:151] op_sel_hi:[1,0]
	v_pk_mul_f32 v[86:87], v[86:87], v[150:151] op_sel_hi:[1,0]
	v_pk_mul_f32 v[76:77], v[76:77], v[150:151] op_sel_hi:[1,0]
	v_pk_mul_f32 v[78:79], v[78:79], v[150:151] op_sel_hi:[1,0]
	v_pk_mul_f32 v[68:69], v[68:69], v[150:151] op_sel_hi:[1,0]
	v_pk_mul_f32 v[70:71], v[70:71], v[150:151] op_sel_hi:[1,0]
	v_pk_mul_f32 v[60:61], v[60:61], v[150:151] op_sel_hi:[1,0]
	v_pk_mul_f32 v[62:63], v[62:63], v[150:151] op_sel_hi:[1,0]
	v_pk_mul_f32 v[52:53], v[52:53], v[150:151] op_sel_hi:[1,0]
	v_pk_mul_f32 v[54:55], v[54:55], v[150:151] op_sel_hi:[1,0]
	v_pk_mul_f32 v[44:45], v[44:45], v[150:151] op_sel_hi:[1,0]
	v_pk_mul_f32 v[46:47], v[46:47], v[150:151] op_sel_hi:[1,0]
	v_pk_mul_f32 v[36:37], v[36:37], v[150:151] op_sel_hi:[1,0]
	v_pk_mul_f32 v[38:39], v[38:39], v[150:151] op_sel_hi:[1,0]
	v_pk_mul_f32 v[90:91], v[90:91], v[152:153] op_sel_hi:[1,0]
	v_pk_mul_f32 v[88:89], v[88:89], v[152:153] op_sel_hi:[1,0]
	v_pk_mul_f32 v[82:83], v[82:83], v[152:153] op_sel_hi:[1,0]
	v_pk_mul_f32 v[80:81], v[80:81], v[152:153] op_sel_hi:[1,0]
	v_pk_mul_f32 v[74:75], v[74:75], v[152:153] op_sel_hi:[1,0]
	v_pk_mul_f32 v[72:73], v[72:73], v[152:153] op_sel_hi:[1,0]
	v_pk_mul_f32 v[66:67], v[66:67], v[152:153] op_sel_hi:[1,0]
	v_pk_mul_f32 v[64:65], v[64:65], v[152:153] op_sel_hi:[1,0]
	v_pk_mul_f32 v[58:59], v[58:59], v[152:153] op_sel_hi:[1,0]
	v_pk_mul_f32 v[56:57], v[56:57], v[152:153] op_sel_hi:[1,0]
	v_pk_mul_f32 v[50:51], v[50:51], v[152:153] op_sel_hi:[1,0]
	v_pk_mul_f32 v[48:49], v[48:49], v[152:153] op_sel_hi:[1,0]
	v_pk_mul_f32 v[42:43], v[42:43], v[152:153] op_sel_hi:[1,0]
	v_pk_mul_f32 v[40:41], v[40:41], v[152:153] op_sel_hi:[1,0]
	v_pk_mul_f32 v[34:35], v[34:35], v[152:153] op_sel_hi:[1,0]
	v_pk_mul_f32 v[32:33], v[32:33], v[152:153] op_sel_hi:[1,0]
	s_branch .LBB0_657

; template <int MODE> ...
;     ...
;       for (int qs = 0; qs < 2; ++qs) {
;         const bool sel = (MODE == 1) ? true : (bool)((mymask[qs] >> j) & 1ull);
;         float mx4[4];
; #pragma unroll
;         for (int mt = 0; mt < 4; ++mt)
;           mx4[mt] = fmaxf(fmaxf(s[qs][mt][0], s[qs][mt][1]), fmaxf(s[qs][mt][2], s[qs][mt][3]));
;         float mx = fmaxf(fmaxf(mx4[0], mx4[1]), fmaxf(mx4[2], mx4[3]));
;         mx = sel ? mx * SCL : -1e30f;
;         mx = quad_max(mx);
;         const float m_new = (mx > m_run[qs] + RESCALE_THR) ? mx : m_run[qs];
;         alpha[qs] = __builtin_amdgcn_exp2f(m_run[qs] - m_new);
;         m_run[qs] = m_new;
;         const float negm = sel ? -m_new : -1e30f;
;         float ps4[4];
; #pragma unroll
;         for (int mt = 0; mt < 4; ++mt) {
; #pragma unroll
;           for (int jj = 0; jj < 4; ++jj) s[qs][mt][jj] = __builtin_amdgcn_exp2f(fmaf(s[qs][mt][jj], SCL, negm));
;           ps4[mt] = (s[qs][mt][0] + s[qs][mt][1]) + (s[qs][mt][2] + s[qs][mt][3]);
;         }
;         l_run[qs] = l_run[qs] * alpha[qs] + ((ps4[0] + ps4[1]) + (ps4[2] + ps4[3]));
; #pragma unroll
;         for (int kk = 0; kk < 2; ++kk) {
;           uint4 pk;
;           pk.x = pack2(s[qs][2 * kk][0], s[qs][2 * kk][1]);
;           pk.y = pack2(s[qs][2 * kk][2], s[qs][2 * kk][3]);
;           pk.z = pack2(s[qs][2 * kk + 1][0], s[qs][2 * kk + 1][1]);
;           pk.w = pack2(s[qs][2 * kk + 1][2], s[qs][2 * kk + 1][3]);
;           pb[qs][kk] = *reinterpret_cast<bf16x8*>(&pk);
;         }
;       }
;       if (__ballot(alpha[0] != 1.0f || alpha[1] != 1.0f) != 0ull) {
; #pragma unroll
;         for (int qs = 0; qs < 2; ++qs)
; #pragma unroll
;           for (int dt = 0; dt < 8; ++dt) {
;             o[qs][dt][0] *= alpha[qs]; o[qs][dt][1] *= alpha[qs]; o[qs][dt][2] *= alpha[qs]; o[qs][dt][3] *= alpha[qs];
;           }
;       }
.LBB0_677:
	v_max_f32_e32 v154, v142, v143
	v_max_f32_e32 v155, v138, v139
	s_nop 0
	v_max_f32_e32 v156, v124, v125
	v_max_f32_e32 v158, v126, v127
	s_nop 0
	v_max_f32_e32 v159, v122, v123
	v_max3_f32 v159, v120, v121, v159
	v_max3_f32 v154, v140, v141, v154
	v_max3_f32 v155, v136, v137, v155
	v_max3_f32 v156, v156, v158, v159
	v_max3_f32 v154, v154, v155, v156
	v_mul_f32_e32 v154, 0x3e0293ee, v154
	v_mov_b32_e32 v155, v154
	s_nop 1
	v_permlane16_swap_b32_e32 v154, v155
	v_max_f32_e32 v154, v154, v155
	v_mov_b32_e32 v155, v154
	s_nop 1
	v_permlane32_swap_b32_e32 v154, v155
	v_max_f32_e32 v156, v154, v155
	v_max_f32_e32 v154, v134, v135
	v_max_f32_e32 v155, v130, v131
	v_max_f32_e32 v158, v112, v113
	v_max_f32_e32 v159, v114, v115
	v_max_f32_e32 v161, v118, v118
	v_max_f32_e32 v160, v161, v119
	v_max3_f32 v160, v116, v117, v160
	v_max3_f32 v154, v132, v133, v154
	v_max3_f32 v155, v128, v129, v155
	v_max3_f32 v158, v158, v159, v160
	v_max3_f32 v154, v154, v155, v158
	v_mul_f32_e32 v154, 0x3e0293ee, v154
	v_mov_b32_e32 v155, v154
	s_nop 1
	v_permlane16_swap_b32_e32 v154, v155
	v_max_f32_e32 v154, v154, v155
	v_mov_b32_e32 v155, v154
	s_nop 1
	v_permlane32_swap_b32_e32 v154, v155
	v_mov_b32_e32 v152, v150
	v_mov_b32_e32 v153, v151
	v_max_f32_e32 v158, v154, v155
	v_add_f32_e32 v154, s48, v152
	v_add_f32_e32 v155, s48, v153
	s_nop 0
	v_cmp_gt_f32_e64 s[6:7], v158, v155
	s_nop 1
	v_cndmask_b32_e64 v151, v151, v158, s[6:7]
	v_cmp_gt_f32_e32 vcc, v156, v154
	s_nop 1
	v_cndmask_b32_e32 v150, v150, v156, vcc
	v_sub_f32_e32 v152, v152, v150
	v_sub_f32_e32 v153, v153, v151
	s_nop 0
	v_exp_f32_e32 v152, v152
	v_exp_f32_e32 v153, v153
	s_or_b64 vcc, vcc, s[6:7]
	s_cbranch_vccz .LBB0_679
	v_mov_b32_e32 v154, v153
	v_pk_mul_f32 v[92:93], v[92:93], v[152:153] op_sel_hi:[1,0]
	v_pk_mul_f32 v[94:95], v[94:95], v[152:153] op_sel_hi:[1,0]
	v_pk_mul_f32 v[88:89], v[88:89], v[152:153] op_sel_hi:[1,0]
	v_pk_mul_f32 v[90:91], v[90:91], v[152:153] op_sel_hi:[1,0]
	v_pk_mul_f32 v[84:85], v[84:85], v[152:153] op_sel_hi:[1,0]
	v_pk_mul_f32 v[86:87], v[86:87], v[152:153] op_sel_hi:[1,0]
	v_pk_mul_f32 v[80:81], v[80:81], v[152:153] op_sel_hi:[1,0]
	v_pk_mul_f32 v[82:83], v[82:83], v[152:153] op_sel_hi:[1,0]
	v_pk_mul_f32 v[76:77], v[76:77], v[152:153] op_sel_hi:[1,0]
	v_pk_mul_f32 v[78:79], v[78:79], v[152:153] op_sel_hi:[1,0]
	v_pk_mul_f32 v[72:73], v[72:73], v[152:153] op_sel_hi:[1,0]
	v_pk_mul_f32 v[74:75], v[74:75], v[152:153] op_sel_hi:[1,0]
	v_pk_mul_f32 v[68:69], v[68:69], v[152:153] op_sel_hi:[1,0]
	v_pk_mul_f32 v[70:71], v[70:71], v[152:153] op_sel_hi:[1,0]
	v_pk_mul_f32 v[64:65], v[64:65], v[152:153] op_sel_hi:[1,0]
	v_pk_mul_f32 v[66:67], v[66:67], v[152:153] op_sel_hi:[1,0]
	v_pk_mul_f32 v[62:63], v[62:63], v[154:155] op_sel_hi:[1,0]
	v_pk_mul_f32 v[60:61], v[60:61], v[154:155] op_sel_hi:[1,0]
	v_pk_mul_f32 v[58:59], v[58:59], v[154:155] op_sel_hi:[1,0]
	v_pk_mul_f32 v[56:57], v[56:57], v[154:155] op_sel_hi:[1,0]
	v_pk_mul_f32 v[54:55], v[54:55], v[154:155] op_sel_hi:[1,0]
	v_pk_mul_f32 v[52:53], v[52:53], v[154:155] op_sel_hi:[1,0]
	v_pk_mul_f32 v[50:51], v[50:51], v[154:155] op_sel_hi:[1,0]
	v_pk_mul_f32 v[48:49], v[48:49], v[154:155] op_sel_hi:[1,0]
	v_pk_mul_f32 v[46:47], v[46:47], v[154:155] op_sel_hi:[1,0]
	v_pk_mul_f32 v[44:45], v[44:45], v[154:155] op_sel_hi:[1,0]
	v_pk_mul_f32 v[42:43], v[42:43], v[154:155] op_sel_hi:[1,0]
	v_pk_mul_f32 v[40:41], v[40:41], v[154:155] op_sel_hi:[1,0]
	v_pk_mul_f32 v[38:39], v[38:39], v[154:155] op_sel_hi:[1,0]
	v_pk_mul_f32 v[36:37], v[36:37], v[154:155] op_sel_hi:[1,0]
	v_pk_mul_f32 v[34:35], v[34:35], v[154:155] op_sel_hi:[1,0]
	v_pk_mul_f32 v[32:33], v[32:33], v[154:155] op_sel_hi:[1,0]
